# queue phases: next work-queue index prefetched one unit ahead (no wait at loop top); LRU pass-3 carry aggregate loads in one window; attention prologue one-window loads
# baseline (speedup 1.0000x reference)
; #define LAS __attribute__((address_space(3)))
; template <class T_> __device__ __forceinline__ T_* as_global(T_* p) { return (T_*)(GAS T_*)p; }
; #define KA() ({ KArgs p_ = (KArgs)__builtin_amdgcn_kernarg_segment_ptr(); asm volatile("" : "+s"(p_)); p_; })
; __global__ void __launch_bounds__(NWAVES * 64, 2) hybrid_fwd(Args args) {
;     ...
;                 KArgs ka = KA(); const LruPtrs lp{as_global(ka->conv_w), as_global(ka->conv_b), as_global(ka->b_lru_r), as_global(ka->b_lru_i), as_global(ka->ws)};
;                 unsigned* qc = (unsigned*)(wsl + WS_CTL) + CW_Q + (chunk * 2 + 0) * 64; LAS unsigned* slot = (LAS unsigned*)(lds + LDSCTL_OFF + 64);
;                 for (;;) {
;                     if (threadIdx.x == 0) *slot = __hip_atomic_fetch_add(qc, 1u, __ATOMIC_RELAXED, __HIP_MEMORY_SCOPE_AGENT);
.LBB0_402:
	s_or_b64 exec, exec, s[4:5]
	s_mov_b64 s[4:5], s[0:1]
	s_lshl_b32 s2, s95, 24
	s_waitcnt lgkmcnt(0)
	s_barrier
	s_add_u32 s77, s36, 0x3200000
	s_load_dwordx4 s[12:15], s[4:5], 0x20
	s_load_dwordx2 s[6:7], s[4:5], 0x38
	s_load_dwordx2 s[8:9], s[4:5], 0x48
	s_load_dwordx2 s[40:41], s[4:5], 0xa0
	s_addc_u32 s33, s37, 0
	s_lshl_b32 s18, s95, 7
	s_lshl_b64 s[4:5], s[18:19], 2
	v_writelane_b32 v255, s2, 8
	s_add_u32 s2, s36, s4
	s_addc_u32 s4, s37, s5
	s_add_u32 s38, s2, 0xc000
	s_addc_u32 s39, s4, 0
	s_lshl_b32 s25, s95, 5
	s_mov_b32 s99, 0
	s_branch .LBB0_406

; __global__ void __launch_bounds__(NWAVES * 64, 2) hybrid_fwd(Args args) {
;     ...
;                 for (;;) {
;                     if (threadIdx.x == 0) *slot = __hip_atomic_fetch_add(qc, 1u, __ATOMIC_RELAXED, __HIP_MEMORY_SCOPE_AGENT);
;                     __syncthreads();
;                     const int L = __builtin_amdgcn_readfirstlane((int)*slot);
;                     __syncthreads();
;                     if (L >= CHB * 16 * 32 + CHB * 16) break;
.LBB0_406:
	s_and_saveexec_b64 s[4:5], s[10:11]
	s_cbranch_execz .LBB0_410
	s_cmp_eq_u32 s99, 0
	s_cbranch_scc0 .Lq2_have
	v_mov_b32_e32 v252, v230
	global_atomic_add v252, v1, v252, s[38:39] sc0
	s_waitcnt vmcnt(0)
.Lq2_have:
	v_mov_b32_e32 v2, s86
	s_nop 0
	ds_write_b32 v2, v252
	s_nop 1
.LBB0_410:
	s_or_b64 exec, exec, s[4:5]
	v_mov_b32_e32 v0, s86
	s_waitcnt lgkmcnt(0)
	s_barrier
	ds_read_b32 v0, v0
	s_mov_b64 s[4:5], -1
	s_waitcnt lgkmcnt(0)
	s_barrier
	v_readfirstlane_b32 s46, v0
	s_cmpk_gt_i32 s46, 0x41f
	s_cbranch_scc1 .LBB0_405
	s_mov_b32 s99, 0
	s_cmpk_lt_i32 s46, 0x2e0
	s_cbranch_scc0 .Lq2_nopf
	s_mov_b32 s99, 1
	s_and_saveexec_b64 s[42:43], s[10:11]
	s_cbranch_execz .Lq2_nopx
	v_mov_b32_e32 v252, v230
	global_atomic_add v252, v1, v252, s[38:39] sc0

; #define LAS __attribute__((address_space(3)))
; __device__ __forceinline__ void cumsum_unit(float* CBh, LAS unsigned char* lds) {
;     int tid_ = threadIdx.x; asm volatile("" : "+v"(tid_));
;     const int tid = tid_, lane = tid & 63, w = tid >> 6;
;     LAS float* wsum = (LAS float*)(lds + RING_OFF + 16384);
;     f32x4 v[4]; float s = 0.f;
; #pragma unroll
;     for (int j = 0; j < 4; ++j) { v[j] = *(const f32x4*)(CBh + tid * 16 + 4 * j);
; #pragma unroll
;         for (int e = 0; e < 4; ++e) { s += v[j][e]; v[j][e] = s; } }
;     float inc = s;
; #pragma unroll
;     for (int d = 1; d < 64; d <<= 1) { const float o = __builtin_bit_cast(float, __builtin_amdgcn_ds_bpermute((lane - d) << 2, __builtin_bit_cast(int, inc))); if (lane >= d) inc += o; }
;     if (lane == 63) wsum[w] = inc;
;     __syncthreads();
;     float off = inc - s;
;     for (int ww = 0; ww < w; ++ww) off += wsum[ww];
; __global__ void __launch_bounds__(NWAVES * 64, 2) hybrid_fwd(Args args) {
;     ...
;                     if (L >= CHB * 16 * 32 + CHB * 16) break;
;                     if (L >= CHB * 16) { const int L1 = L - CHB * 16; lru_unit<1>(lp, lds, chunk, L1 >> 9, (L1 >> 5) & 15, L1 & 31); }
;                     else cumsum_unit(CB + (size_t)(chunk * CHB * 16 + L) * T, lds);
.Lq2_nopf:
	s_cmp_lt_i32 s46, 32
	s_cbranch_scc0 .LBB0_419
	s_add_i32 s4, s46, s25
	s_ashr_i32 s5, s4, 31
	s_lshl_b64 s[4:5], s[4:5], 15
	v_mov_b32_e32 v28, v236
	s_add_u32 s4, s77, s4
	s_addc_u32 s5, s33, s5
	v_lshlrev_b32_e32 v2, 4, v28
	v_ashrrev_i32_e32 v3, 31, v2
	v_lshl_add_u64 v[2:3], v[2:3], 2, s[4:5]
	global_load_dwordx4 v[4:7], v[2:3], off
	global_load_dwordx4 v[8:11], v[2:3], off offset:16
	global_load_dwordx4 v[20:23], v[2:3], off offset:32
	global_load_dwordx4 v[24:27], v[2:3], off offset:48
	v_and_b32_e32 v0, 63, v28
	v_lshlrev_b32_e32 v29, 2, v0
	v_add_u32_e32 v30, -4, v29
	v_cmp_eq_u32_e32 vcc, 0, v0
	s_waitcnt vmcnt(3)
	v_add_f32_e32 v18, 0, v4
	v_add_f32_e32 v19, v5, v18
	v_add_f32_e32 v16, v6, v19
	v_add_f32_e32 v17, v7, v16
	s_waitcnt vmcnt(2)
	v_add_f32_e32 v14, v8, v17
	v_add_f32_e32 v15, v9, v14
	v_add_f32_e32 v12, v10, v15
	v_add_f32_e32 v13, v11, v12
	s_waitcnt vmcnt(1)
	v_add_f32_e32 v10, v20, v13
	v_add_f32_e32 v11, v21, v10
	v_add_f32_e32 v8, v22, v11
	v_add_f32_e32 v9, v23, v8
	s_waitcnt vmcnt(0)
	v_add_f32_e32 v6, v24, v9
	v_add_f32_e32 v7, v25, v6
	v_add_f32_e32 v4, v26, v7
	v_add_f32_e32 v5, v27, v4
	ds_bpermute_b32 v20, v30, v5
	v_add_u32_e32 v21, -8, v29
	v_add_u32_e32 v22, -16, v29
	s_waitcnt lgkmcnt(0)
	v_add_f32_e32 v20, v5, v20
	v_cndmask_b32_e32 v20, v20, v5, vcc
	ds_bpermute_b32 v21, v21, v20
	v_cmp_gt_u32_e32 vcc, 2, v0
	s_waitcnt lgkmcnt(0)
	v_add_f32_e32 v21, v20, v21
	v_cndmask_b32_e32 v20, v21, v20, vcc
	ds_bpermute_b32 v21, v22, v20
	v_cmp_gt_u32_e32 vcc, 4, v0
	v_subrev_u32_e32 v22, 32, v29
	s_waitcnt lgkmcnt(0)
	v_add_f32_e32 v21, v20, v21
	v_cndmask_b32_e32 v20, v21, v20, vcc
	ds_bpermute_b32 v21, v22, v20
	v_cmp_gt_u32_e32 vcc, 8, v0
	v_subrev_u32_e32 v22, 64, v29
	s_waitcnt lgkmcnt(0)
	v_add_f32_e32 v21, v20, v21
	v_cndmask_b32_e32 v20, v21, v20, vcc
	ds_bpermute_b32 v21, v22, v20
	v_cmp_gt_u32_e32 vcc, 16, v0
	v_add_u32_e32 v22, 0xffffff80, v29
	s_waitcnt lgkmcnt(0)
	v_add_f32_e32 v21, v20, v21
	v_cndmask_b32_e32 v21, v21, v20, vcc
	ds_bpermute_b32 v22, v22, v21
	v_ashrrev_i32_e32 v20, 6, v28
	v_cmp_eq_u32_e32 vcc, 63, v0
	s_waitcnt lgkmcnt(0)
	v_add_f32_e32 v22, v21, v22
	s_and_saveexec_b64 s[4:5], vcc
	v_lshl_add_u32 v23, v20, 2, 0
	ds_write_b32 v23, v22 offset:16384
	s_or_b64 exec, exec, s[4:5]
	v_cmp_gt_u32_e32 vcc, 32, v0
	s_waitcnt lgkmcnt(0)
	s_barrier
	v_cndmask_b32_e32 v0, v22, v21, vcc
	v_sub_f32_e32 v0, v0, v5
	v_cmp_lt_i32_e32 vcc, 0, v20
	s_and_saveexec_b64 s[4:5], vcc
	s_cbranch_execz .LBB0_418
	s_add_i32 s2, 0, 0x4000
	s_mov_b64 s[42:43], 0

.LBB0_449:
	s_waitcnt vmcnt(0)
	s_add_u32 s46, s36, 0x2a00000
	s_addc_u32 s47, s37, 0
	v_mov_b32_e32 v10, v236
	s_cmpk_lt_i32 s96, 0x100
	s_mov_b32 s17, s91
	s_cselect_b64 s[6:7], -1, 0
	s_cmpk_gt_i32 s96, 0xff
	v_readfirstlane_b32 s2, v10
	s_cbranch_scc1 .LBB0_451
	s_ashr_i32 s4, s96, 7
	s_ashr_i32 s5, s4, 31
	s_lshl_b64 s[8:9], s[4:5], 24
	s_add_u32 s5, s93, s8
	s_addc_u32 s8, s16, s9
	s_lshl_b32 s9, s96, 19
	s_and_b32 s9, s9, 0xf80000
	s_add_u32 s5, s5, s9
	s_addc_u32 s8, s8, 0
	s_lshl_b32 s9, s96, 4
	s_and_b32 s9, s9, 0x600
	s_add_u32 s5, s5, s9
	s_addc_u32 s8, s8, 0
	s_add_u32 s42, s5, 0xc000000
	s_addc_u32 s43, s8, 0
	s_lshl_b32 s5, s95, 9
	s_lshl_b32 s4, s4, 8
	s_add_i32 s4, s4, s5
	s_ashr_i32 s5, s4, 31
	s_lshl_b64 s[4:5], s[4:5], 11
	s_add_u32 s4, s46, s4
	s_addc_u32 s5, s47, s5
	s_add_u32 s90, s4, s9
	s_addc_u32 s91, s5, 0

; #define LAS __attribute__((address_space(3)))
; template <class T_> __device__ __forceinline__ T_* as_global(T_* p) { return (T_*)(GAS T_*)p; }
; #define KA() ({ KArgs p_ = (KArgs)__builtin_amdgcn_kernarg_segment_ptr(); asm volatile("" : "+s"(p_)); p_; })
; __global__ void __launch_bounds__(NWAVES * 64, 2) hybrid_fwd(Args args) {
;     ...
;                 KArgs ka = KA(); const LruPtrs lp{as_global(ka->conv_w), as_global(ka->conv_b), as_global(ka->b_lru_r), as_global(ka->b_lru_i), as_global(ka->ws)};
;                 unsigned* qc = (unsigned*)(wsl + WS_CTL) + CW_Q + (chunk * 2 + 1) * 64; LAS unsigned* slot = (LAS unsigned*)(lds + LDSCTL_OFF + 64);
;                 for (;;) {
.LBB0_533:
	s_or_b64 exec, exec, s[6:7]
	s_add_u32 s54, s36, 0x10000
	s_addc_u32 s55, s37, 0
	s_add_u32 s56, s36, 0x17c00000
	s_addc_u32 s57, s37, 0
	s_add_u32 s58, s36, 0x19c00000
	s_addc_u32 s59, s37, 0
	s_mov_b64 s[6:7], s[0:1]
	s_add_u32 s60, s36, 0x1bc00000
	s_waitcnt lgkmcnt(0)
	s_barrier
	s_load_dwordx2 s[12:13], s[6:7], 0xa0
	s_addc_u32 s61, s37, 0
	s_add_u32 s62, s36, 0x1dc00000
	s_addc_u32 s63, s37, 0
	s_add_u32 s64, s36, 0x32000fc
	s_addc_u32 s65, s37, 0
	s_mov_b32 s99, 0
	s_branch .LBB0_537

; __global__ void __launch_bounds__(NWAVES * 64, 2) hybrid_fwd(Args args) {
;     ...
;                 for (;;) {
;                     if (threadIdx.x == 0) *slot = __hip_atomic_fetch_add(qc, 1u, __ATOMIC_RELAXED, __HIP_MEMORY_SCOPE_AGENT);
.LBB0_537:
	s_and_saveexec_b64 s[6:7], s[10:11]
	s_cbranch_execz .LBB0_541
	s_cmp_eq_u32 s99, 0
	s_cbranch_scc0 .Lq3_have
	v_mov_b32_e32 v252, v230
	global_atomic_add v252, v1, v252, s[38:39] offset:256 sc0
	s_waitcnt vmcnt(0)

; __global__ void __launch_bounds__(NWAVES * 64, 2) hybrid_fwd(Args args) {
;     ...
;                     __syncthreads();
;                     const int L = __builtin_amdgcn_readfirstlane((int)*slot);
;                     __syncthreads();
;                     if (L >= 2 * CHB * 16 * 32) break;
.LBB0_541:
	s_or_b64 exec, exec, s[6:7]
	v_mov_b32_e32 v0, s86
	s_waitcnt lgkmcnt(0)
	s_barrier
	ds_read_b32 v0, v0
	s_mov_b64 s[6:7], -1
	s_waitcnt lgkmcnt(0)
	s_barrier
	v_readfirstlane_b32 s2, v0
	s_cmpk_gt_i32 s2, 0x7ff
	s_cbranch_scc1 .LBB0_536
	s_mov_b32 s99, 0
	s_cmpk_lt_i32 s2, 0x6c0
	s_cbranch_scc0 .Lq3_nopf
	s_mov_b32 s99, 1
	s_and_saveexec_b64 s[8:9], s[10:11]
	s_cbranch_execz .Lq3_nopx
	v_mov_b32_e32 v252, v230
	global_atomic_add v252, v1, v252, s[38:39] offset:256 sc0

; #define GAS __attribute__((address_space(1)))
; template <int PASS>
; __device__ __forceinline__ void lru_unit(const LruPtrs& args, LAS unsigned char* lds, int chunk, int bl, int g, int ck) {
;     ...
;         for (int i = 0; i < 4; ++i) { const int idx = lane + 64 * i, r = idx >> 3, ch = idx & 7;
;             gtile[i] = *(const GAS v4u*)(Z + ((size_t)bl * T + ck * 256 + w * 32 + r) * LDZ + ZC_GA + g * 64 + ch * 8); }
; #pragma unroll
;         for (int q = 0; q < 8; ++q) { const v4u st = stash[q * 64];
; #pragma unroll
;             for (int p = 0; p < 4; ++p) { av[q][p] = pg8::bf_lo(st[p]); uv[q][p] = pg8::bf_hi(st[p]); } }
;         if (w == 0) { const GAS unsigned* gs = (const GAS unsigned*)((GAS v4u*)(ws + WS_STASH) + ((size_t)((bl * 16 + g) * 32 + ck) * NWAVES) * 8 * 64);
; #pragma unroll
;             for (int ww = 0; ww < 8; ++ww) gagg[ww] = gs[(size_t)((ww * 8 + (lane >> 3)) * 64 + 31 + 32 * ((lane >> 2) & 1)) * 4 + (lane & 3)]; }
; __global__ void __launch_bounds__(NWAVES * 64, 2) hybrid_fwd(Args args) {
;     ...
;                     else { const int L3 = L - CHB * 16 * 32; lru_unit<3>(lp, lds, chunk, L3 >> 9, (L3 >> 5) & 15, L3 & 31); }
.Lq3_nopf:
	s_cmpk_gt_i32 s2, 0x3ff
	s_cbranch_scc0 .LBB0_557
	v_mov_b32_e32 v68, v236
	s_add_i32 s18, s2, 0xfffffc00
	s_lshr_b32 s41, s18, 9
	v_readfirstlane_b32 s15, v68
	s_bfe_u32 s42, s2, 0x40005
	s_and_b32 s40, s2, 31
	s_ashr_i32 s14, s15, 6
	s_mov_b64 s[8:9], s[12:13]
	s_add_u32 s6, s8, 0x13c00000
	s_addc_u32 s7, s9, 0
	s_add_u32 s43, s8, 0x29c00000
	s_addc_u32 s44, s9, 0
	s_and_b32 s18, s18, 0x1ffffe00
	s_lshl_b32 s45, s42, 5
	s_or_b32 s18, s45, s18
	s_or_b32 s18, s18, s40
	s_lshl_b32 s18, s18, 3
	s_ashr_i32 s45, s14, 31
	s_add_u32 s46, s14, s18
	s_addc_u32 s47, s45, 0
	s_lshl_b32 s45, s40, 8
	s_lshl_b32 s48, s14, 5
	s_lshl_b32 s49, s41, 13
	s_lshl_b64 s[46:47], s[46:47], 13
	s_or_b32 s45, s49, s45
	s_ashr_i32 s49, s48, 31
	s_add_u32 s45, s48, s45
	s_addc_u32 s48, s49, 0
	v_bfe_u32 v69, v68, 3, 3
	v_or_b32_e32 v2, s45, v69
	v_mov_b32_e32 v3, s48
	v_lshlrev_b32_e32 v0, 3, v68
	v_lshlrev_b64 v[4:5], 11, v[2:3]
	v_and_b32_e32 v0, 56, v0
	v_lshl_add_u64 v[4:5], s[6:7], 0, v[4:5]
	s_lshl_b32 s48, s42, 7
	s_mov_b32 s49, s19
	v_or_b32_e32 v6, 8, v2
	v_mov_b32_e32 v7, v3
	v_lshl_add_u64 v[4:5], v[4:5], 0, s[48:49]
	v_lshlrev_b32_e32 v0, 1, v0
	v_lshlrev_b64 v[6:7], 11, v[6:7]
	v_lshl_add_u64 v[52:53], v[4:5], 0, v[0:1]
	v_lshl_add_u64 v[6:7], s[6:7], 0, v[6:7]
	v_add_co_u32_e32 v4, vcc, s88, v52
	v_lshl_add_u64 v[6:7], v[6:7], 0, s[48:49]
	s_nop 0
	v_addc_co_u32_e32 v5, vcc, 0, v53, vcc
	v_lshl_add_u64 v[54:55], v[6:7], 0, v[0:1]
	v_add_co_u32_e32 v6, vcc, s88, v54
	v_and_b32_e32 v70, 63, v68
	s_nop 0
	v_addc_co_u32_e32 v7, vcc, 0, v55, vcc
	global_load_dwordx4 v[30:33], v[4:5], off
	global_load_dwordx4 v[34:37], v[6:7], off
	v_or_b32_e32 v4, 16, v2
	v_mov_b32_e32 v5, v3
	v_lshlrev_b64 v[4:5], 11, v[4:5]
	v_lshl_add_u64 v[4:5], s[6:7], 0, v[4:5]
	v_or_b32_e32 v2, 24, v2
	v_lshl_add_u64 v[4:5], v[4:5], 0, s[48:49]
	v_lshlrev_b64 v[2:3], 11, v[2:3]
	v_lshl_add_u64 v[56:57], v[4:5], 0, v[0:1]
	v_lshl_add_u64 v[2:3], s[6:7], 0, v[2:3]
	v_add_co_u32_e32 v4, vcc, s88, v56
	v_lshl_add_u64 v[2:3], v[2:3], 0, s[48:49]
	s_nop 0
	v_addc_co_u32_e32 v5, vcc, 0, v57, vcc
	v_lshl_add_u64 v[50:51], v[2:3], 0, v[0:1]
	v_add_co_u32_e32 v2, vcc, s88, v50
	s_add_u32 s6, s43, s46
	s_nop 0
	v_addc_co_u32_e32 v3, vcc, 0, v51, vcc
	global_load_dwordx4 v[42:45], v[4:5], off
	global_load_dwordx4 v[46:49], v[2:3], off
	s_addc_u32 s7, s44, s47
	v_lshlrev_b32_e32 v2, 4, v70
	v_mov_b32_e32 v3, v1
	v_lshl_add_u64 v[4:5], s[6:7], 0, v[2:3]
	global_load_dwordx4 v[38:41], v2, s[6:7]
	global_load_dwordx4 v[26:29], v2, s[6:7] offset:1024
	global_load_dwordx4 v[22:25], v2, s[6:7] offset:2048
	global_load_dwordx4 v[18:21], v2, s[6:7] offset:3072
	v_add_co_u32_e32 v2, vcc, 0x1000, v4
	s_cmp_lt_u32 s15, 64
	s_nop 0
	v_addc_co_u32_e32 v3, vcc, 0, v5, vcc
	global_load_dwordx4 v[14:17], v[2:3], off
	global_load_dwordx4 v[10:13], v[2:3], off offset:1024
	global_load_dwordx4 v[6:9], v[2:3], off offset:2048
	s_nop 0
	global_load_dwordx4 v[2:5], v[2:3], off offset:3072
	v_mov_b32_e32 v59, 0
	s_cselect_b64 s[6:7], -1, 0
	s_cmp_gt_u32 s15, 63
	v_mov_b32_e32 v77, 0
	v_mov_b32_e32 v75, 0
	v_mov_b32_e32 v74, 0
	v_mov_b32_e32 v73, 0
	v_mov_b32_e32 v72, 0
	v_mov_b32_e32 v71, 0
	v_mov_b32_e32 v76, 0
	s_cbranch_scc1 .LBB0_545
	v_lshlrev_b32_e32 v58, 5, v70
	v_lshlrev_b32_e32 v60, 5, v68
	s_lshl_b64 s[46:47], s[18:19], 13
	v_and_b32_e32 v58, 0x700, v58
	v_and_b32_e32 v60, 0x80, v60
	v_and_b32_e32 v61, 3, v68
	s_add_u32 s46, s43, s46
	v_or3_b32 v58, v60, v61, v58
	s_addc_u32 s47, s44, s47
	v_lshlrev_b32_e32 v60, 2, v58
	v_mov_b32_e32 v61, v1
	v_lshl_add_u64 v[62:63], s[46:47], 0, v[60:61]
	s_movk_i32 s18, 0x2000
	v_add_co_u32_e32 v64, vcc, s18, v62
	s_movk_i32 s18, 0x6000
	s_nop 0
	v_addc_co_u32_e32 v65, vcc, 0, v63, vcc
	v_add_co_u32_e32 v66, vcc, s31, v62
	s_nop 1
	v_addc_co_u32_e32 v67, vcc, 0, v63, vcc
	v_add_co_u32_e32 v72, vcc, s18, v62
	s_nop 1
	v_addc_co_u32_e32 v73, vcc, 0, v63, vcc
	v_add_co_u32_e32 v78, vcc, 0x8000, v62
	s_nop 1
	v_addc_co_u32_e32 v79, vcc, 0, v63, vcc
	v_add_co_u32_e32 v80, vcc, 0xa000, v62
	s_nop 1
	v_addc_co_u32_e32 v81, vcc, 0, v63, vcc
	v_add_co_u32_e32 v62, vcc, 0xc000, v62
	s_nop 1
	v_addc_co_u32_e32 v63, vcc, 0, v63, vcc
	global_load_dword v77, v60, s[46:47] offset:496
	global_load_dword v75, v[64:65], off offset:496
	global_load_dword v74, v[66:67], off offset:496
	s_nop 0
	global_load_dword v73, v[72:73], off offset:496
	s_nop 0
	global_load_dword v72, v[78:79], off offset:496
	global_load_dword v71, v[80:81], off offset:496
	global_load_dword v76, v[62:63], off offset:496

; #define GAS __attribute__((address_space(1)))
; template <int PASS>
; __device__ __forceinline__ void lru_unit(const LruPtrs& args, LAS unsigned char* lds, int chunk, int bl, int g, int ck) {
;     ...
;     if (PASS == 3) { typedef float f32x2v __attribute__((ext_vector_type(2))); f32x2v ag[4];
; #pragma unroll
;         for (int j = 0; j < 4; ++j) { const int cc = 4 * w + j; ag[j] = (f32x2v){1.f, 0.f}; if (cc < ck) ag[j] = *(const GAS f32x2v*)(AGG + ((size_t)(bl * 32 + cc) * D + g * 64 + lane) * 2); }
; #pragma unroll
;         for (int j = 0; j < 4; ++j) { pH = ag[j].x * pH + ag[j].y; pA = pA * ag[j].x; } }
;     ...
;     if (PASS == 3) { PART[(w * 64 + lane) * 2] = pA; PART[(w * 64 + lane) * 2 + 1] = pH; }
;     __syncthreads();
;     if (PASS == 1) {
;         if (w == 0) { float A = 1.f, H = 0.f;
; #pragma unroll
;             for (int ww = 0; ww < 8; ++ww) { const float a = WAG[(ww * 64 + lane) * 2], h = WAG[(ww * 64 + lane) * 2 + 1]; H = a * H + h; A = A * a; }
;             GAS float* dst = AGG + ((size_t)(bl * 32 + ck) * D + g * 64 + lane) * 2; dst[0] = A; dst[1] = H; }
;         __syncthreads();
;     } else {
;         if (w == 0) { float H = 0.f;
; #pragma unroll
;             for (int ww = 0; ww < 8; ++ww) H = PART[(ww * 64 + lane) * 2] * H + PART[(ww * 64 + lane) * 2 + 1];
; #pragma unroll
;             for (int ww = 0; ww < 8; ++ww) { CARW[ww * 64 + lane] = H; H = pg8::bf_lo(gagg[ww]) * H + pg8::bf_hi(gagg[ww]); } }
.LBB0_550:
	s_or_b32 s41, s42, 2
	v_mov_b32_e32 v65, 0
	v_mov_b32_e32 v61, 1.0
	s_cmp_ge_i32 s41, s40
	v_mov_b32_e32 v60, 1.0
	v_mov_b32_e32 v67, 0
	v_mov_b32_e32 v66, 1.0
	v_mov_b32_e32 v90, 1.0
	v_mov_b32_e32 v91, 0
	s_cbranch_scc1 .LBB0_552
	s_add_i32 s44, s41, s18
	s_ashr_i32 s45, s44, 31
	s_lshl_b64 s[44:45], s[44:45], 13
	s_add_u32 s44, s8, s44
	s_addc_u32 s45, s9, s45
	global_load_dwordx2 v[66:67], v64, s[44:45]
.LBB0_552:
	s_or_b32 s41, s42, 3
	s_cmp_ge_i32 s41, s40
	s_cbranch_scc1 .LBB0_554
	s_add_i32 s40, s41, s18
	s_ashr_i32 s41, s40, 31
	s_lshl_b64 s[40:41], s[40:41], 13
	s_add_u32 s8, s8, s40
	s_addc_u32 s9, s9, s41
	global_load_dwordx2 v[90:91], v64, s[8:9]
.LBB0_554:
	s_waitcnt vmcnt(0)
	v_mov_b32_e32 v60, v66
	v_mov_b32_e32 v61, v90
	v_mov_b32_e32 v65, v91
	v_fmac_f32_e32 v59, 0, v58
	v_fmac_f32_e32 v63, v62, v59
	s_andn2_b32 s15, s15, 63
	v_mul_f32_e32 v66, v58, v62
	v_fmac_f32_e32 v67, v60, v63
	v_or_b32_e32 v58, s15, v70
	v_lshl_add_u32 v62, v58, 3, 0
	v_pk_mul_f32 v[58:59], v[60:61], v[66:67]
	v_mov_b32_e32 v64, v61
	v_pk_mul_f32 v[58:59], v[64:65], v[58:59]
	v_pk_fma_f32 v[60:61], v[60:61], v[66:67], v[64:65]
	s_andn2_b64 vcc, exec, s[6:7]
	v_mov_b32_e32 v59, v61
	ds_write_b64 v62, v[58:59] offset:4096
	s_waitcnt lgkmcnt(0)
	s_barrier
	s_cbranch_vccnz .LBB0_556
	v_lshl_add_u32 v66, v70, 3, 0
	ds_read2st64_b64 v[58:61], v66 offset0:8 offset1:9
	ds_read2st64_b64 v[62:65], v66 offset0:10 offset1:11
	ds_read2st64_b64 v[78:81], v66 offset0:12 offset1:13
	ds_read2st64_b64 v[82:85], v66 offset0:14 offset1:15
	v_lshlrev_b32_e32 v67, 2, v70
	s_waitcnt lgkmcnt(3)
	v_fma_f32 v58, 0, v58, v59
	v_fmac_f32_e32 v61, v58, v60
	s_waitcnt lgkmcnt(2)
	v_fma_f32 v58, v61, v62, v63
	v_fmac_f32_e32 v65, v58, v64
	s_waitcnt lgkmcnt(1)
	v_fma_f32 v58, v65, v78, v79
	v_fmac_f32_e32 v81, v58, v80
	s_waitcnt lgkmcnt(0)
	v_fma_f32 v58, v81, v82, v83
	v_fmac_f32_e32 v85, v58, v84
	v_lshlrev_b32_e32 v59, 16, v77
	v_and_b32_e32 v60, 0xffff0000, v77
	v_sub_u32_e32 v58, v66, v67
	v_fmac_f32_e32 v60, v85, v59
	v_lshlrev_b32_e32 v59, 16, v75
	v_and_b32_e32 v61, 0xffff0000, v75
	ds_write2st64_b32 v58, v85, v60 offset0:32 offset1:33
	v_fmac_f32_e32 v61, v60, v59
	v_lshlrev_b32_e32 v59, 16, v74
	v_and_b32_e32 v60, 0xffff0000, v74
	v_fmac_f32_e32 v60, v61, v59
	ds_write2st64_b32 v58, v61, v60 offset0:34 offset1:35
	v_lshlrev_b32_e32 v59, 16, v73
	v_and_b32_e32 v61, 0xffff0000, v73
	v_fmac_f32_e32 v61, v60, v59
	v_lshlrev_b32_e32 v59, 16, v72
	v_and_b32_e32 v60, 0xffff0000, v72
	v_fmac_f32_e32 v60, v61, v59
	ds_write2st64_b32 v58, v61, v60 offset0:36 offset1:37
	v_lshlrev_b32_e32 v59, 16, v71
	v_and_b32_e32 v61, 0xffff0000, v71
	v_fmac_f32_e32 v61, v60, v59
	v_lshlrev_b32_e32 v59, 16, v76
	v_and_b32_e32 v60, 0xffff0000, v76
	v_fmac_f32_e32 v60, v61, v59
	ds_write2st64_b32 v58, v61, v60 offset0:38 offset1:39

; #define PG8_STAGE(bufoff, gbase, voff) do { _Pragma("unroll") for (int _i = 0; _i < 2; ++_i) \
;         __builtin_amdgcn_global_load_lds((const unsigned*)((const char*)(gbase) + (voff)[_i]), (PG8_LAS unsigned*)(lds + (bufoff) + ldsw + _i * 8192), 16, 0, 0); } while (0)
; #define PG8_BAR __builtin_amdgcn_s_barrier()
; template <class Epi, class Sched>
; __device__ __forceinline__ void gemm_phase(PG8_LAS unsigned char* lds, const Gemm g, const Sched& S, const Epi& E) {
;     ...
;     const int tid = tid_, wid = __builtin_amdgcn_readfirstlane(tid >> 6), lane = tid & 63, wr = wid >> 2, wc = wid & 3, fr = lane & 15, fq = lane >> 4;
;     const int K = g.K, nt = K / BK;
;     unsigned voffA[2], voffB[2];
; #pragma unroll
;     for (int i = 0; i < 2; ++i) { int R, C; stage_rc(tid * 16 + i * 8192, R, C); const int Rb = (R & ~31) + perm32(R & 31);
;         voffA[i] = (unsigned)(R * g.lda + C) * 2u; voffB[i] = (unsigned)(Rb * g.ldb + C) * 2u; }
;     const size_t kstep = (size_t)(BK * 2);
;     const size_t hstepA = (size_t)HALF * g.lda * 2, hstepB = (size_t)HALF * g.ldb * 2;
;     const unsigned ldsw = (unsigned)wid * 1024u;
;     const int aoff = lds_byte(wr * 64 + fr, fq * 8), boff = lds_byte(wc * 32 + fr, fq * 8);
;     ...
;     Unit cur, nxt; int ui = 0;
;     if (!S.next(0, cur)) return;
;     f32x4 acc[2][2][4][2];
; #pragma unroll
;     for (int a = 0; a < 2; ++a)
; #pragma unroll
;         for (int b = 0; b < 2; ++b)
; #pragma unroll
;             for (int m = 0; m < 4; ++m)
; #pragma unroll
;                 for (int n = 0; n < 2; ++n) acc[a][b][m][n] = (f32x4){0.f, 0.f, 0.f, 0.f};
;     bf16x8 At[4][2], B0[2][2], B1[2][2];
;     const char* cA = (const char*)cur.A; const char* cB = (const char*)cur.B;
;     PG8_STAGE(PG8_SB(0, 0), cB, voffB); PG8_STAGE(PG8_SB(0, 1), cB + hstepB, voffB); PG8_STAGE(PG8_SA(0, 0), cA, voffA); PG8_STAGE(PG8_SA(0, 1), cA + hstepA, voffA);
;     if (wr == 1) PG8_BAR;
.LBB0_691:
	s_waitcnt vmcnt(0)
	v_mov_b32_e32 v10, v236
	s_and_b64 vcc, exec, s[4:5]
	v_readfirstlane_b32 s2, v10
	s_movk_i32 s77, 0x161
	s_cbranch_vccnz .LBB0_705
	v_lshlrev_b32_e32 v0, 4, v10
	v_add_u32_e32 v2, 0x2000, v0
	v_ashrrev_i32_e32 v3, 31, v2
	v_lshrrev_b32_e32 v3, 22, v3
	v_add_u32_e32 v3, v2, v3
	v_ashrrev_i32_e32 v3, 10, v3
	v_mul_i32_i24_e32 v4, 0x400, v3
	v_sub_u32_e32 v2, v2, v4
	v_lshrrev_b32_e32 v4, 4, v2
	v_bitop3_b32 v2, v4, v2, 32 bitop3:0x6c
	v_ashrrev_i32_e32 v4, 31, v2
	v_lshrrev_b32_e32 v4, 26, v4
	v_add_u32_e32 v4, v2, v4
	v_lshlrev_b32_e32 v6, 3, v3
	v_ashrrev_i32_e32 v5, 6, v4
	v_and_b32_e32 v6, -16, v6
	v_and_b32_e32 v4, 0xc0, v4
	v_add_u32_e32 v6, v5, v6
	v_sub_u32_e32 v2, v2, v4
	v_and_b32_e32 v5, 3, v5
	s_mov_b32 s6, 0x7fffe0
	v_lshrrev_b32_e32 v7, 2, v6
	v_lshlrev_b32_e32 v8, 1, v6
	v_lshlrev_b32_e32 v3, 5, v3
	v_ashrrev_i16_sdwa v2, v230, sext(v2) dst_sel:DWORD dst_unused:UNUSED_PAD src0_sel:DWORD src1_sel:BYTE_0
	v_and_or_b32 v5, v6, s6, v5
	v_and_b32_e32 v7, 4, v7
	v_and_b32_e32 v8, 24, v8
	v_and_b32_e32 v3, 32, v3
	v_bfe_i32 v2, v2, 0, 16
	v_or3_b32 v5, v5, v7, v8
	v_add_lshl_u32 v2, v3, v2, 1
	v_lshl_add_u32 v162, v5, 9, v2
	v_lshl_add_u32 v164, v6, 11, v2
	v_bfe_i32 v2, v10, 27, 1
	v_lshrrev_b32_e32 v2, 22, v2
	v_add_u32_e32 v2, v0, v2
	v_and_b32_e32 v2, 0xfffffc00, v2
	v_sub_u32_e32 v0, v0, v2
	v_lshrrev_b32_e32 v2, 4, v0
	v_ashrrev_i32_e32 v4, 31, v10
	v_bitop3_b32 v0, v2, v0, 32 bitop3:0x6c
	v_lshrrev_b32_e32 v4, 26, v4
	v_ashrrev_i32_e32 v2, 31, v0
	v_add_u32_e32 v4, v10, v4
	v_lshrrev_b32_e32 v2, 26, v2
	v_ashrrev_i32_e32 v4, 6, v4
	s_ashr_i32 s8, s2, 6
	v_add_u32_e32 v2, v0, v2
	v_lshlrev_b32_e32 v5, 3, v4
	s_ashr_i32 s9, s2, 8
	s_lshl_b32 s25, s8, 10
	v_ashrrev_i32_e32 v3, 6, v2
	v_and_b32_e32 v5, -16, v5
	s_add_u32 s33, s36, 0x2e00000
	v_add_u32_e32 v5, v3, v5
	v_and_b32_e32 v3, 3, v3
	s_addc_u32 s48, s37, 0
	v_and_or_b32 v3, v5, s6, v3
	s_ashr_i32 s6, s96, 7
	s_ashr_i32 s7, s6, 31
	s_bfe_u32 s15, s96, 0x20005
	s_lshl_b64 s[12:13], s[6:7], 24
	s_add_u32 s7, s93, s12
	s_addc_u32 s13, s16, s13
	s_lshl_b32 s12, s96, 19
	s_and_b32 s12, s12, 0xf80000
	s_add_u32 s12, s7, s12
	s_addc_u32 s13, s13, 0
	s_lshl_b32 s14, s15, 8
	s_lshl_b32 s7, s15, 9
	s_add_u32 s18, s12, s7
	s_addc_u32 s38, s13, 0
	s_add_u32 s42, s18, 0xc000000
	s_addc_u32 s43, s38, 0
	s_lshl_b32 s49, s95, 1
	s_add_i32 s6, s6, s49
	s_ashr_i32 s7, s6, 31
	v_and_b32_e32 v2, 0xc0, v2
	s_lshl_b64 s[6:7], s[6:7], 19
	v_sub_u32_e32 v0, v0, v2
	s_add_u32 s6, s33, s6
	v_lshrrev_b32_e32 v6, 2, v5
	v_lshlrev_b32_e32 v7, 1, v5
	v_lshlrev_b32_e32 v4, 5, v4
	v_ashrrev_i16_sdwa v0, v230, sext(v0) dst_sel:DWORD dst_unused:UNUSED_PAD src0_sel:DWORD src1_sel:BYTE_0
	s_addc_u32 s7, s48, s7
	s_lshl_b32 s15, s15, 17
	v_and_b32_e32 v6, 4, v6
	v_and_b32_e32 v7, 24, v7
	v_and_b32_e32 v4, 32, v4
	v_bfe_i32 v0, v0, 0, 16
	s_add_u32 s46, s6, s15
	v_or3_b32 v3, v3, v6, v7
	v_add_lshl_u32 v2, v4, v0, 1
	s_addc_u32 s47, s7, 0
	s_add_i32 s50, s25, 0
	v_lshl_add_u32 v0, v3, 9, v2
	s_add_i32 m0, s50, 0x10000
	v_lshl_add_u32 v166, v5, 11, v2
	global_load_lds_dwordx4 v0, s[46:47]
	s_add_i32 m0, s50, 0x12000
	s_add_u32 s6, s46, 0x10000
	global_load_lds_dwordx4 v162, s[46:47]
	s_addc_u32 s7, s47, 0
	s_add_i32 m0, s50, 0x14000
	s_add_i32 s51, s50, 0x2000
	global_load_lds_dwordx4 v0, s[6:7]
	s_add_i32 m0, s50, 0x16000
	v_mov_b32_e32 v163, v1
	global_load_lds_dwordx4 v162, s[6:7]
	s_mov_b32 m0, s50
	s_add_u32 s6, s18, 0xc040000
	global_load_lds_dwordx4 v166, s[42:43]
	s_mov_b32 m0, s51
	s_addc_u32 s7, s38, 0
	s_add_i32 s52, s50, 0x4000
	global_load_lds_dwordx4 v164, s[42:43]
	s_mov_b32 m0, s52
	s_add_i32 s53, s50, 0x6000
	global_load_lds_dwordx4 v166, s[6:7]
	s_mov_b32 m0, s53
	v_mov_b32_e32 v167, v1
	global_load_lds_dwordx4 v164, s[6:7]
	v_mov_b32_e32 v165, v1
	s_cmp_eq_u32 s9, 1
	v_mov_b32_e32 v254, 1
	v_lshl_add_u64 v[8:9], s[46:47], 0, v[0:1]
	v_lshl_add_u64 v[6:7], s[46:47], 0, v[162:163]
	v_lshl_add_u64 v[2:3], s[42:43], 0, v[166:167]
	s_cselect_b64 s[6:7], -1, 0
	s_cmp_lg_u32 s9, 1
	v_lshl_add_u64 v[4:5], s[42:43], 0, v[164:165]
	s_cbranch_scc1 .LBB0_694
	s_barrier
